# PLE-gate layer1 third round runs after the last grid barrier on 16 CUs that then exit; the other 240 CUs do the final RMSNorm and poll a flag before sample rows
# baseline (speedup 1.0000x reference)
;     __device__ __forceinline__ bool next(int i, Unit& u) const {
;         constexpr int NU = (33792 / BM) * NN;
;         const int L = i * G + ((NU - i * G < G) ? vp : v); if (L >= NU) return false;
;         constexpr int NM = 33792 / BM, NFULL = (NM / 8) * 8 * NN;
;         if (L < NFULL) { const int g = L / (8 * NN), idx = L % (8 * NN); u.pm = g * 8 + (idx & 7); u.pn = idx >> 3; }
;         else { constexpr int GS = NM % 8 ? NM % 8 : 8; const int idx = L - NFULL; u.pm = (NM / 8) * 8 + idx % GS; u.pn = idx / GS; }
.LBB0_1348:
	s_or_b64 exec, exec, s[6:7]
	s_mov_b32 s65, 0
	s_mov_b32 s66, s4
	s_mov_b32 s71, s86
	s_barrier
.Lp6b_entry:
	s_and_b64 vcc, exec, s[74:75]
	s_cbranch_vccz .LBB0_1353
	s_and_b64 vcc, exec, s[74:75]
	s_mov_b32 s2, s86
	s_cbranch_vccz .LBB0_1354
.LBB0_1350:
	v_readlane_b32 s0, v249, 17
	v_readlane_b32 s1, v249, 18
	s_and_b64 s[0:1], s[0:1], exec
	s_cselect_b32 s3, s2, s86
	s_cmp_eq_u32 s65, 1
	s_cbranch_scc0 .Lp6b_f0
	s_add_i32 s3, s71, 0x110
.Lp6b_f0:
	s_cmpk_lt_i32 s3, 0x210
	v_mov_b32_e32 v0, v196
	s_cselect_b64 s[0:1], -1, 0
	s_cmpk_gt_i32 s3, 0x20f
	s_cbranch_scc1 .LBB0_1357
	s_cmpk_gt_i32 s3, 0x1ff
	s_cbranch_scc0 .LBB0_1355
	s_add_i32 s5, s3, 0xfffffe00
	s_and_b32 s6, s3, 3
	s_or_b32 s36, s6, 0x80
	s_lshr_b32 s30, s5, 2
	s_cbranch_execz .LBB0_1356
	s_branch .LBB0_1357

;     __device__ __forceinline__ bool next(int i, Unit& u) const {
;         constexpr int NU = (33792 / BM) * NN;
;         const int L = i * G + ((NU - i * G < G) ? vp : v); if (L >= NU) return false;
;         constexpr int NM = 33792 / BM, NFULL = (NM / 8) * 8 * NN;
;         if (L < NFULL) { const int g = L / (8 * NN), idx = L % (8 * NN); u.pm = g * 8 + (idx & 7); u.pn = idx >> 3; }
;         else { constexpr int GS = NM % 8 ? NM % 8 : 8; const int idx = L - NFULL; u.pm = (NM / 8) * 8 + idx % GS; u.pn = idx / GS; }
.LBB0_1363:
	s_add_i32 s49, s49, 1
	s_mul_i32 s11, s49, s64
	s_sub_i32 s13, 0x210, s11
	s_cmp_lt_i32 s13, s64
	s_cselect_b32 s13, s2, s86
	s_add_i32 s11, s13, s11
	s_cmp_lg_u32 s64, 0x100
	s_cbranch_scc1 .Lp6b_s
	s_cmp_eq_u32 s65, 1
	s_cbranch_scc1 .Lp6b_none
	s_cmpk_lt_i32 s11, 0x200
	s_cbranch_scc1 .Lp6b_s
.Lp6b_none:
	s_movk_i32 s11, 0x210
.Lp6b_s:
	s_cmpk_lt_i32 s11, 0x210
	s_cselect_b64 s[14:15], -1, 0
	s_cmpk_gt_i32 s11, 0x20f
	s_cbranch_scc1 .LBB0_1368
	s_cmpk_gt_i32 s11, 0x1ff
	s_mov_b64 s[16:17], -1
	s_cbranch_scc0 .LBB0_1366
	s_add_i32 s12, s11, 0xfffffe00
	s_and_b32 s10, s11, 3
	s_bitset1_b32 s10, 7
	s_lshr_b32 s12, s12, 2
	s_mov_b64 s[16:17], 0

; __device__ __forceinline__ void grid_bar(unsigned* bar, unsigned k, unsigned G, unsigned bid, bool leader) {
;     asm volatile("s_waitcnt vmcnt(0) lgkmcnt(0)" ::: "memory");
;     __syncthreads();
;     if (leader) {
.LBB0_1392:
	s_cmp_eq_u32 s65, 1
	s_cbranch_scc1 .Lp6b_done2
	v_readlane_b32 s0, v249, 54
	v_readlane_b32 s1, v249, 55
	s_and_b64 vcc, exec, s[0:1]
	s_mov_b64 s[2:3], 0
	s_cbranch_vccnz .LBB0_1394
	v_mov_b32_e32 v0, v196
	s_nop 0
	v_cmp_eq_u32_e32 vcc, 0, v0
	s_and_b64 s[2:3], vcc, exec

; __device__ __forceinline__ int lane_id() { int l = __builtin_amdgcn_mbcnt_hi(~0u, __builtin_amdgcn_mbcnt_lo(~0u, 0u)); asm volatile("" : "+v"(l)); return l; }
; __device__ __forceinline__ void grid_bar(unsigned* bar, unsigned k, unsigned G, unsigned bid, bool leader) {
;     ...
;     __syncthreads();
; }
; __global__ void __launch_bounds__(NWAVES * 64, 2) mega_fwd(Args args) {
;     ...
;     {
;         const int lane = lane_id();
;         const int gw = bid * NWAVES + wave, NGW = G * NWAVES;
;         const float* ssq = (const float*)(ws + WS_SSQ) + 4 * (size_t)MT;
;         const float* g_fin = (const float*)(ws + WS_SMALL) + SM_GFIN;
;         const bf16* XB = (const bf16*)(ws + WS_XB);
;         f32x4 gf[2][2];
; #pragma unroll
;         for (int j = 0; j < 2; ++j) { gf[j][0] = *(const f32x4*)(g_fin + j * 512 + lane * 8); gf[j][1] = *(const f32x4*)(g_fin + j * 512 + lane * 8 + 4); }
;         for (int m = gw; m < MT; m += NGW) {
;             const float rstd = __builtin_amdgcn_rsqf(ssq[m] * (1.0f / DM) + EPS);
;             float* yr = H + (size_t)m * DM;
; #pragma unroll
;             for (int j = 0; j < 2; ++j) {
;                 const v4u w = *(const v4u*)(XB + (size_t)m * DM + j * 512 + lane * 8);
;                 const f32x4 a = (f32x4){bf_lo(w.x), bf_hi(w.x), bf_lo(w.y), bf_hi(w.y)}, b2 = (f32x4){bf_lo(w.z), bf_hi(w.z), bf_lo(w.w), bf_hi(w.w)};
;                 *(f32x4*)(yr + j * 512 + lane * 8) = a * rstd * gf[j][0]; *(f32x4*)(yr + j * 512 + lane * 8 + 4) = b2 * rstd * gf[j][1];
;             }
.LBB0_1409:
	s_or_b64 exec, exec, s[0:1]
	s_barrier
	s_cmp_lg_u32 s64, 0x100
	s_cbranch_scc1 .Lp6b_after
	s_cmp_lg_u32 s65, 0
	s_cbranch_scc1 .Lp6b_after
	s_cmp_lt_u32 s71, 0xf0
	s_cbranch_scc1 .Lp6b_after
	s_mov_b32 s4, s66
	s_mov_b32 s86, s71
	s_mov_b32 s65, 1
	s_branch .Lp6b_entry
.Lp6b_done2:
	v_readlane_b32 s68, v249, 1
	v_readlane_b32 s69, v249, 2
	s_waitcnt vmcnt(0) lgkmcnt(0)
	v_readlane_b32 s67, v249, 0
	s_nop 3
	s_cmp_lg_u32 s67, 0
	s_cbranch_scc1 .Lp6b_rel_done
	buffer_wbl2 sc1
	s_waitcnt vmcnt(0)
	v_mov_b32_e32 v4, 0
	v_mov_b32_e32 v5, 1
	s_mov_b64 s[70:71], exec
	s_mov_b64 exec, 1
	global_atomic_add v4, v5, s[68:69] offset:3468
	s_waitcnt vmcnt(0)
	s_mov_b64 exec, s[70:71]
.Lp6b_rel_done:
	s_mov_b32 s65, 2
	s_endpgm
.Lp6b_after:
	s_cmp_lg_u32 s64, 0x100
	s_cbranch_scc1 .Lp6b_a2
	s_movk_i32 s12, 0x780
.Lp6b_a2:
	v_readlane_b32 s0, v249, 15
	v_readlane_b32 s1, v249, 16
	v_readlane_b32 s6, v249, 1
	s_andn2_b64 vcc, exec, s[0:1]
	v_readlane_b32 s7, v249, 2
	s_cbranch_vccnz .LBB0_1412
	v_lshlrev_b32_e32 v16, 3, v196
	v_ashrrev_i32_e32 v17, 31, v16
	v_lshlrev_b64 v[18:19], 2, v[16:17]
	v_lshl_add_u64 v[0:1], s[6:7], 0, v[18:19]
	v_add_co_u32_e32 v22, vcc, 0xca000, v0
	s_mov_b64 s[0:1], 0xca500
	s_nop 0
	v_addc_co_u32_e32 v23, vcc, 0, v1, vcc
	v_lshl_add_u64 v[20:21], v[0:1], 0, s[0:1]
	global_load_dwordx4 v[0:3], v[22:23], off offset:1280
	global_load_dwordx4 v[4:7], v[20:21], off offset:2064
	global_load_dwordx4 v[8:11], v[20:21], off offset:16
	global_load_dwordx4 v[12:15], v[20:21], off offset:2048
	s_ashr_i32 s35, s34, 31
	s_lshl_b64 s[0:1], s[34:35], 2
	s_add_u32 s0, s6, s0
	s_addc_u32 s1, s7, s1
	s_add_u32 s0, s0, 0x85000
	s_addc_u32 s1, s1, 0
	s_ashr_i32 s13, s12, 31
	s_lshl_b64 s[2:3], s[12:13], 2
	s_lshl_b64 s[4:5], s[34:35], 11
	s_add_u32 s4, s6, s4
	s_addc_u32 s5, s7, s5
	v_lshl_add_u64 v[16:17], v[16:17], 1, s[4:5]
	s_mov_b64 s[4:5], 0x3600000
	v_readlane_b32 s8, v249, 3
	v_lshl_add_u64 v[16:17], v[16:17], 0, s[4:5]
	s_lshl_b64 s[4:5], s[12:13], 11
	s_lshl_b64 s[6:7], s[34:35], 12
	v_readlane_b32 s10, v249, 5
	v_readlane_b32 s11, v249, 6
	s_add_u32 s6, s10, s6
	s_addc_u32 s7, s11, s7
	v_lshl_add_u64 v[18:19], s[6:7], 0, v[18:19]
	s_mov_b64 s[6:7], 0x800
	v_lshl_add_u64 v[18:19], v[18:19], 0, s[6:7]
	s_lshl_b64 s[6:7], s[12:13], 12
	v_mov_b32_e32 v20, 0
	v_mov_b32_e32 v21, 0x358637bd
	v_readlane_b32 s9, v249, 4
.LBB0_1411:
	global_load_dword v34, v20, s[0:1]
	global_load_dwordx4 v[36:39], v[16:17], off
	global_load_dwordx4 v[40:43], v[16:17], off offset:1024
	s_add_i32 s34, s34, s12
	s_add_u32 s0, s0, s2
	s_addc_u32 s1, s1, s3
	v_lshl_add_u64 v[16:17], v[16:17], 0, s[4:5]
	s_cmp_lt_u32 s34, 0x8000
	s_cbranch_scc1 .Lfin_np1
	s_cmp_gt_u32 s34, 0x83ff
	s_cbranch_scc1 .Lfin_np1
	s_cmp_lg_u32 s64, 0x100
	s_cbranch_scc1 .Lfin_np1
	v_readlane_b32 s14, v249, 1
	v_readlane_b32 s15, v249, 2
	s_nop 4
.Lfin_np1_poll:
	global_load_dword v60, v20, s[14:15] offset:3468 sc1
	s_waitcnt vmcnt(0)
	v_readfirstlane_b32 s16, v60
	s_nop 0
	s_cmp_ge_u32 s16, 16
	s_cbranch_scc1 .Lfin_np1_ok
	s_sleep 2
	s_branch .Lfin_np1_poll

; __global__ void __launch_bounds__(NWAVES * 64, 2) mega_fwd(Args args) {
;     ...
;         for (int m = gw; m < MT; m += NGW) {
;             const float rstd = __builtin_amdgcn_rsqf(ssq[m] * (1.0f / DM) + EPS);
;             float* yr = H + (size_t)m * DM;
; #pragma unroll
;             for (int j = 0; j < 2; ++j) {
;                 const v4u w = *(const v4u*)(XB + (size_t)m * DM + j * 512 + lane * 8);
;                 const f32x4 a = (f32x4){bf_lo(w.x), bf_hi(w.x), bf_lo(w.y), bf_hi(w.y)}, b2 = (f32x4){bf_lo(w.z), bf_hi(w.z), bf_lo(w.w), bf_hi(w.w)};
;                 *(f32x4*)(yr + j * 512 + lane * 8) = a * rstd * gf[j][0]; *(f32x4*)(yr + j * 512 + lane * 8 + 4) = b2 * rstd * gf[j][1];
;             }
.Lfin_np1:
	s_cmp_gt_i32 s34, 0x83ff
	s_cbranch_scc1 .Lfin_tailA
	global_load_dword v35, v20, s[0:1]
	global_load_dwordx4 v[44:47], v[16:17], off
	global_load_dwordx4 v[48:51], v[16:17], off offset:1024
	s_waitcnt vmcnt(3)
	v_fmamk_f32 v30, v34, 0x3a800000, v21
	v_rsq_f32_e32 v30, v30
	v_lshlrev_b32_e32 v26, 16, v36
	v_and_b32_e32 v27, 0xffff0000, v36
	v_lshlrev_b32_e32 v22, 16, v37
	v_and_b32_e32 v23, 0xffff0000, v37
	v_lshlrev_b32_e32 v28, 16, v38
	v_and_b32_e32 v29, 0xffff0000, v38
	v_lshlrev_b32_e32 v24, 16, v39
	v_and_b32_e32 v25, 0xffff0000, v39
	v_pk_mul_f32 v[26:27], v[30:31], v[26:27] op_sel_hi:[0,1]
	v_pk_mul_f32 v[22:23], v[30:31], v[22:23] op_sel_hi:[0,1]
	v_pk_mul_f32 v[32:33], v[30:31], v[28:29] op_sel_hi:[0,1]
	v_pk_mul_f32 v[28:29], v[30:31], v[24:25] op_sel_hi:[0,1]
	v_pk_mul_f32 v[24:25], v[2:3], v[22:23]
	v_pk_mul_f32 v[22:23], v[0:1], v[26:27]
	v_pk_mul_f32 v[28:29], v[10:11], v[28:29]
	v_pk_mul_f32 v[26:27], v[8:9], v[32:33]
	global_store_dwordx4 v[18:19], v[22:25], off offset:-2048
	global_store_dwordx4 v[18:19], v[26:29], off offset:-2032
	v_lshlrev_b32_e32 v56, 16, v40
	v_and_b32_e32 v57, 0xffff0000, v40
	v_lshlrev_b32_e32 v52, 16, v41
	v_and_b32_e32 v53, 0xffff0000, v41
	v_lshlrev_b32_e32 v58, 16, v42
	v_and_b32_e32 v59, 0xffff0000, v42
	v_lshlrev_b32_e32 v54, 16, v43
	v_and_b32_e32 v55, 0xffff0000, v43
	v_pk_mul_f32 v[56:57], v[30:31], v[56:57] op_sel_hi:[0,1]
	v_pk_mul_f32 v[52:53], v[30:31], v[52:53] op_sel_hi:[0,1]
	v_pk_mul_f32 v[62:63], v[30:31], v[58:59] op_sel_hi:[0,1]
	v_pk_mul_f32 v[58:59], v[30:31], v[54:55] op_sel_hi:[0,1]
	v_pk_mul_f32 v[54:55], v[14:15], v[52:53]
	v_pk_mul_f32 v[52:53], v[12:13], v[56:57]
	v_pk_mul_f32 v[58:59], v[6:7], v[58:59]
	v_pk_mul_f32 v[56:57], v[4:5], v[62:63]
	global_store_dwordx4 v[18:19], v[52:55], off
	global_store_dwordx4 v[18:19], v[56:59], off offset:16
	v_lshl_add_u64 v[18:19], v[18:19], 0, s[6:7]
.Lfin_loop:
	s_add_i32 s34, s34, s12
	s_add_u32 s0, s0, s2
	s_addc_u32 s1, s1, s3
	v_lshl_add_u64 v[16:17], v[16:17], 0, s[4:5]
	s_cmp_lt_u32 s34, 0x8000
	s_cbranch_scc1 .Lfin_np2
	s_cmp_gt_u32 s34, 0x83ff
	s_cbranch_scc1 .Lfin_np2
	s_cmp_lg_u32 s64, 0x100
	s_cbranch_scc1 .Lfin_np2
	v_readlane_b32 s14, v249, 1
	v_readlane_b32 s15, v249, 2
	s_nop 4

; __global__ void __launch_bounds__(NWAVES * 64, 2) mega_fwd(Args args) {
;     ...
;         for (int m = gw; m < MT; m += NGW) {
;             const float rstd = __builtin_amdgcn_rsqf(ssq[m] * (1.0f / DM) + EPS);
;             float* yr = H + (size_t)m * DM;
; #pragma unroll
;             for (int j = 0; j < 2; ++j) {
;                 const v4u w = *(const v4u*)(XB + (size_t)m * DM + j * 512 + lane * 8);
;                 const f32x4 a = (f32x4){bf_lo(w.x), bf_hi(w.x), bf_lo(w.y), bf_hi(w.y)}, b2 = (f32x4){bf_lo(w.z), bf_hi(w.z), bf_lo(w.w), bf_hi(w.w)};
;                 *(f32x4*)(yr + j * 512 + lane * 8) = a * rstd * gf[j][0]; *(f32x4*)(yr + j * 512 + lane * 8 + 4) = b2 * rstd * gf[j][1];
;             }
.Lfin_np2:
	s_cmp_gt_i32 s34, 0x83ff
	s_cbranch_scc1 .Lfin_tailB
	global_load_dword v34, v20, s[0:1]
	global_load_dwordx4 v[36:39], v[16:17], off
	global_load_dwordx4 v[40:43], v[16:17], off offset:1024
	s_waitcnt vmcnt(7)
	v_fmamk_f32 v30, v35, 0x3a800000, v21
	v_rsq_f32_e32 v30, v30
	v_lshlrev_b32_e32 v26, 16, v44
	v_and_b32_e32 v27, 0xffff0000, v44
	v_lshlrev_b32_e32 v22, 16, v45
	v_and_b32_e32 v23, 0xffff0000, v45
	v_lshlrev_b32_e32 v28, 16, v46
	v_and_b32_e32 v29, 0xffff0000, v46
	v_lshlrev_b32_e32 v24, 16, v47
	v_and_b32_e32 v25, 0xffff0000, v47
	v_pk_mul_f32 v[26:27], v[30:31], v[26:27] op_sel_hi:[0,1]
	v_pk_mul_f32 v[22:23], v[30:31], v[22:23] op_sel_hi:[0,1]
	v_pk_mul_f32 v[32:33], v[30:31], v[28:29] op_sel_hi:[0,1]
	v_pk_mul_f32 v[28:29], v[30:31], v[24:25] op_sel_hi:[0,1]
	v_pk_mul_f32 v[24:25], v[2:3], v[22:23]
	v_pk_mul_f32 v[22:23], v[0:1], v[26:27]
	v_pk_mul_f32 v[28:29], v[10:11], v[28:29]
	v_pk_mul_f32 v[26:27], v[8:9], v[32:33]
	global_store_dwordx4 v[18:19], v[22:25], off offset:-2048
	global_store_dwordx4 v[18:19], v[26:29], off offset:-2032
	v_lshlrev_b32_e32 v56, 16, v48
	v_and_b32_e32 v57, 0xffff0000, v48
	v_lshlrev_b32_e32 v52, 16, v49
	v_and_b32_e32 v53, 0xffff0000, v49
	v_lshlrev_b32_e32 v58, 16, v50
	v_and_b32_e32 v59, 0xffff0000, v50
	v_lshlrev_b32_e32 v54, 16, v51
	v_and_b32_e32 v55, 0xffff0000, v51
	v_pk_mul_f32 v[56:57], v[30:31], v[56:57] op_sel_hi:[0,1]
	v_pk_mul_f32 v[52:53], v[30:31], v[52:53] op_sel_hi:[0,1]
	v_pk_mul_f32 v[62:63], v[30:31], v[58:59] op_sel_hi:[0,1]
	v_pk_mul_f32 v[58:59], v[30:31], v[54:55] op_sel_hi:[0,1]
	v_pk_mul_f32 v[54:55], v[14:15], v[52:53]
	v_pk_mul_f32 v[52:53], v[12:13], v[56:57]
	v_pk_mul_f32 v[58:59], v[6:7], v[58:59]
	v_pk_mul_f32 v[56:57], v[4:5], v[62:63]
	global_store_dwordx4 v[18:19], v[52:55], off
	global_store_dwordx4 v[18:19], v[56:59], off offset:16
	v_lshl_add_u64 v[18:19], v[18:19], 0, s[6:7]
	s_add_i32 s34, s34, s12
	s_add_u32 s0, s0, s2
	s_addc_u32 s1, s1, s3
	v_lshl_add_u64 v[16:17], v[16:17], 0, s[4:5]
	s_cmp_lt_u32 s34, 0x8000
	s_cbranch_scc1 .Lfin_np3
	s_cmp_gt_u32 s34, 0x83ff
	s_cbranch_scc1 .Lfin_np3
	s_cmp_lg_u32 s64, 0x100
	s_cbranch_scc1 .Lfin_np3
	v_readlane_b32 s14, v249, 1
	v_readlane_b32 s15, v249, 2
	s_nop 4

; __global__ void __launch_bounds__(NWAVES * 64, 2) mega_fwd(Args args) {
;     ...
;         for (int m = gw; m < MT; m += NGW) {
;             const float rstd = __builtin_amdgcn_rsqf(ssq[m] * (1.0f / DM) + EPS);
;             float* yr = H + (size_t)m * DM;
; #pragma unroll
;             for (int j = 0; j < 2; ++j) {
;                 const v4u w = *(const v4u*)(XB + (size_t)m * DM + j * 512 + lane * 8);
;                 const f32x4 a = (f32x4){bf_lo(w.x), bf_hi(w.x), bf_lo(w.y), bf_hi(w.y)}, b2 = (f32x4){bf_lo(w.z), bf_hi(w.z), bf_lo(w.w), bf_hi(w.w)};
;                 *(f32x4*)(yr + j * 512 + lane * 8) = a * rstd * gf[j][0]; *(f32x4*)(yr + j * 512 + lane * 8 + 4) = b2 * rstd * gf[j][1];
;             }
.Lfin_np3:
	s_cmp_gt_i32 s34, 0x83ff
	s_cbranch_scc1 .Lfin_tailA
	global_load_dword v35, v20, s[0:1]
	global_load_dwordx4 v[44:47], v[16:17], off
	global_load_dwordx4 v[48:51], v[16:17], off offset:1024
	s_waitcnt vmcnt(7)
	v_fmamk_f32 v30, v34, 0x3a800000, v21
	v_rsq_f32_e32 v30, v30
	v_lshlrev_b32_e32 v26, 16, v36
	v_and_b32_e32 v27, 0xffff0000, v36
	v_lshlrev_b32_e32 v22, 16, v37
	v_and_b32_e32 v23, 0xffff0000, v37
	v_lshlrev_b32_e32 v28, 16, v38
	v_and_b32_e32 v29, 0xffff0000, v38
	v_lshlrev_b32_e32 v24, 16, v39
	v_and_b32_e32 v25, 0xffff0000, v39
	v_pk_mul_f32 v[26:27], v[30:31], v[26:27] op_sel_hi:[0,1]
	v_pk_mul_f32 v[22:23], v[30:31], v[22:23] op_sel_hi:[0,1]
	v_pk_mul_f32 v[32:33], v[30:31], v[28:29] op_sel_hi:[0,1]
	v_pk_mul_f32 v[28:29], v[30:31], v[24:25] op_sel_hi:[0,1]
	v_pk_mul_f32 v[24:25], v[2:3], v[22:23]
	v_pk_mul_f32 v[22:23], v[0:1], v[26:27]
	v_pk_mul_f32 v[28:29], v[10:11], v[28:29]
	v_pk_mul_f32 v[26:27], v[8:9], v[32:33]
	global_store_dwordx4 v[18:19], v[22:25], off offset:-2048
	global_store_dwordx4 v[18:19], v[26:29], off offset:-2032
	v_lshlrev_b32_e32 v56, 16, v40
	v_and_b32_e32 v57, 0xffff0000, v40
	v_lshlrev_b32_e32 v52, 16, v41
	v_and_b32_e32 v53, 0xffff0000, v41
	v_lshlrev_b32_e32 v58, 16, v42
	v_and_b32_e32 v59, 0xffff0000, v42
	v_lshlrev_b32_e32 v54, 16, v43
	v_and_b32_e32 v55, 0xffff0000, v43
	v_pk_mul_f32 v[56:57], v[30:31], v[56:57] op_sel_hi:[0,1]
	v_pk_mul_f32 v[52:53], v[30:31], v[52:53] op_sel_hi:[0,1]
	v_pk_mul_f32 v[62:63], v[30:31], v[58:59] op_sel_hi:[0,1]
	v_pk_mul_f32 v[58:59], v[30:31], v[54:55] op_sel_hi:[0,1]
	v_pk_mul_f32 v[54:55], v[14:15], v[52:53]
	v_pk_mul_f32 v[52:53], v[12:13], v[56:57]
	v_pk_mul_f32 v[58:59], v[6:7], v[58:59]
	v_pk_mul_f32 v[56:57], v[4:5], v[62:63]
	global_store_dwordx4 v[18:19], v[52:55], off
	global_store_dwordx4 v[18:19], v[56:59], off offset:16
	v_lshl_add_u64 v[18:19], v[18:19], 0, s[6:7]
	s_branch .Lfin_loop
